# v45 + W_in GEMM: waves owning only zero-weight padding columns (tile pn=1, bj=1 half, wc 1..3) skip those MFMAs and fragment reads after the peeled first iteration
# baseline (speedup 1.0000x reference)
.LBB0_683:
	s_ashr_i32 s5, s4, 31
	s_lshl_b64 s[38:39], s[4:5], 19
	v_readlane_b32 s16, v244, 44
	v_readlane_b32 s17, v244, 45
	s_add_u32 s72, s16, s38
	s_addc_u32 s73, s17, s39
	s_and_b64 s[38:39], s[6:7], exec
	s_cselect_b32 s5, s73, s11
	s_cselect_b32 s38, s72, s10
	s_ashr_i32 s13, s12, 31
	s_lshl_b64 s[42:43], s[12:13], 19
	s_add_u32 s70, s3, s42
	s_addc_u32 s71, s34, s43
	s_and_b64 s[42:43], s[6:7], exec
	s_cselect_b32 s13, s71, s87
	s_cselect_b32 s39, s70, s86
	s_lshl_b32 s44, s52, 10
	s_lshl_b32 s42, s4, 8
	s_add_i32 s53, s44, 0
	s_ashr_i32 s43, s42, 31
	s_add_i32 s53, s53, 0x20800
	s_add_u32 s10, s10, 0x40080
	s_addc_u32 s11, s11, 0
	s_add_u32 s68, s86, 0x100
	v_add_u32_e32 v245, 0x10000, v213
	v_add_u32_e32 v246, 0x10000, v214
	s_mov_b32 s100, 1
	s_waitcnt vmcnt(0)
	v_lshl_add_u64 v[130:131], s[42:43], 2, v[172:173]
	s_addc_u32 s69, s87, 0
	v_readfirstlane_b32 s101, v0
	s_bfe_u32 s101, s101, 0x20006
	s_cmp_eq_u32 s14, 1
	s_cselect_b32 s101, s101, 0
	s_mov_b32 s42, -2
	s_branch .LBB0_685
.LBB0_684:
	s_cmp_lg_u32 s100, 0
	s_cbranch_scc1 .Lpeel_2
	ds_read_b128 v[132:135], v245
	ds_read_b128 v[136:139], v246
	ds_read_b128 v[140:143], v245 offset:2048
	ds_read_b128 v[144:147], v246 offset:2048
	s_cmp_lg_u32 s101, 0
	s_cbranch_scc1 .Lpad_r1
	ds_read_b128 v[148:151], v245 offset:16384
	ds_read_b128 v[152:155], v246 offset:16384
	ds_read_b128 v[156:159], v245 offset:18432
	ds_read_b128 v[160:163], v246 offset:18432
.Lpad_r1:
	s_add_u32 s43, s10, 0xfffc0080
	s_addc_u32 s46, s11, -1
	s_and_b64 s[44:45], s[86:87], exec
	s_cselect_b32 vcc_hi, s5, s46
	s_cselect_b32 vcc_lo, s38, s43
	s_cselect_b32 s87, s13, s69
	s_cselect_b32 s86, s39, s68
	s_add_i32 m0, s88, 0xc000
	ds_read_b128 v[164:167], v215
	s_waitcnt lgkmcnt(0)
	ds_read_b128 v[190:193], v215 offset:2048
	ds_read_b128 v[194:197], v216
	ds_read_b128 v[198:201], v216 offset:2048
	ds_read_b128 v[202:205], v215 offset:4096
	ds_read_b128 v[206:209], v215 offset:6144
	ds_read_b128 v[218:221], v216 offset:4096
	ds_read_b128 v[222:225], v216 offset:6144
	global_load_lds_dwordx4 v180, s[10:11]
	s_add_i32 m0, s88, 0xe000
	s_nop 0
	global_load_lds_dwordx4 v184, s[10:11]
	s_waitcnt vmcnt(8)
	s_waitcnt lgkmcnt(0)
	s_barrier
	s_setprio 1
	s_waitcnt lgkmcnt(0)
	v_mfma_f32_16x16x32_bf16 v[126:129], v[132:135], v[164:167], v[126:129]
	v_mfma_f32_16x16x32_bf16 v[126:129], v[136:139], v[194:197], v[126:129]
	v_mfma_f32_16x16x32_bf16 v[122:125], v[140:143], v[164:167], v[122:125]
	v_mfma_f32_16x16x32_bf16 v[122:125], v[144:147], v[194:197], v[122:125]
	v_mfma_f32_16x16x32_bf16 v[110:113], v[132:135], v[190:193], v[110:113]
	v_mfma_f32_16x16x32_bf16 v[110:113], v[136:139], v[198:201], v[110:113]
	v_mfma_f32_16x16x32_bf16 v[106:109], v[140:143], v[190:193], v[106:109]
	v_mfma_f32_16x16x32_bf16 v[106:109], v[144:147], v[198:201], v[106:109]
	v_mfma_f32_16x16x32_bf16 v[94:97], v[132:135], v[202:205], v[94:97]
	v_mfma_f32_16x16x32_bf16 v[94:97], v[136:139], v[218:221], v[94:97]
	v_mfma_f32_16x16x32_bf16 v[90:93], v[140:143], v[202:205], v[90:93]
	v_mfma_f32_16x16x32_bf16 v[90:93], v[144:147], v[218:221], v[90:93]
	v_mfma_f32_16x16x32_bf16 v[78:81], v[132:135], v[206:209], v[78:81]
	v_mfma_f32_16x16x32_bf16 v[78:81], v[136:139], v[222:225], v[78:81]
	v_mfma_f32_16x16x32_bf16 v[74:77], v[140:143], v[206:209], v[74:77]
	v_mfma_f32_16x16x32_bf16 v[74:77], v[144:147], v[222:225], v[74:77]
	s_setprio 0
	s_setprio 1
	s_cmp_lg_u32 s101, 0
	s_cbranch_scc1 .Lpad_m1
	v_mfma_f32_16x16x32_bf16 v[118:121], v[148:151], v[164:167], v[118:121]
	v_mfma_f32_16x16x32_bf16 v[118:121], v[152:155], v[194:197], v[118:121]
	v_mfma_f32_16x16x32_bf16 v[114:117], v[156:159], v[164:167], v[114:117]
	v_mfma_f32_16x16x32_bf16 v[114:117], v[160:163], v[194:197], v[114:117]
	v_mfma_f32_16x16x32_bf16 v[102:105], v[148:151], v[190:193], v[102:105]
	v_mfma_f32_16x16x32_bf16 v[102:105], v[152:155], v[198:201], v[102:105]
	v_mfma_f32_16x16x32_bf16 v[98:101], v[156:159], v[190:193], v[98:101]
	v_mfma_f32_16x16x32_bf16 v[98:101], v[160:163], v[198:201], v[98:101]
	v_mfma_f32_16x16x32_bf16 v[86:89], v[148:151], v[202:205], v[86:89]
	v_mfma_f32_16x16x32_bf16 v[86:89], v[152:155], v[218:221], v[86:89]
	v_mfma_f32_16x16x32_bf16 v[82:85], v[156:159], v[202:205], v[82:85]
	v_mfma_f32_16x16x32_bf16 v[82:85], v[160:163], v[218:221], v[82:85]
	v_mfma_f32_16x16x32_bf16 v[70:73], v[148:151], v[206:209], v[70:73]
	v_mfma_f32_16x16x32_bf16 v[70:73], v[152:155], v[222:225], v[70:73]
	v_mfma_f32_16x16x32_bf16 v[66:69], v[156:159], v[206:209], v[66:69]
	v_mfma_f32_16x16x32_bf16 v[66:69], v[160:163], v[222:225], v[66:69]
.Lpad_m1:
	s_setprio 0
	s_barrier
	s_add_i32 s43, s78, s15
	s_mov_b32 m0, s43
	ds_read_b128 v[164:167], v215 offset:16384
	ds_read_b128 v[190:193], v215 offset:18432
	ds_read_b128 v[194:197], v216 offset:16384
	ds_read_b128 v[198:201], v216 offset:18432
	ds_read_b128 v[202:205], v215 offset:20480
	ds_read_b128 v[206:209], v215 offset:22528
	ds_read_b128 v[218:221], v216 offset:20480
	ds_read_b128 v[222:225], v216 offset:22528
	global_load_lds_dwordx4 v170, s[86:87]
	s_add_i32 m0, s43, 0x2000
	s_add_u32 s44, s86, 0x40000
	s_addc_u32 s45, s87, 0
	s_add_i32 s43, s82, s15
	global_load_lds_dwordx4 v178, s[86:87]
	s_mov_b32 m0, s43
	s_nop 0
	global_load_lds_dwordx4 v170, s[44:45]
	s_add_i32 m0, s43, 0x2000
	s_nop 0
	global_load_lds_dwordx4 v178, s[44:45]
	s_mov_b32 m0, s88
	s_nop 0
	global_load_lds_dwordx4 v174, vcc
	s_mov_b32 m0, s89
	s_nop 0
	global_load_lds_dwordx4 v176, vcc
	s_waitcnt vmcnt(8)
	s_waitcnt lgkmcnt(0)
	s_barrier
	s_setprio 1
	s_waitcnt lgkmcnt(0)
	v_mfma_f32_16x16x32_bf16 v[62:65], v[132:135], v[164:167], v[62:65]
	v_mfma_f32_16x16x32_bf16 v[62:65], v[136:139], v[194:197], v[62:65]
	v_mfma_f32_16x16x32_bf16 v[58:61], v[140:143], v[164:167], v[58:61]
	v_mfma_f32_16x16x32_bf16 v[58:61], v[144:147], v[194:197], v[58:61]
	v_mfma_f32_16x16x32_bf16 v[46:49], v[132:135], v[190:193], v[46:49]
	v_mfma_f32_16x16x32_bf16 v[46:49], v[136:139], v[198:201], v[46:49]
	v_mfma_f32_16x16x32_bf16 v[42:45], v[140:143], v[190:193], v[42:45]
	v_mfma_f32_16x16x32_bf16 v[42:45], v[144:147], v[198:201], v[42:45]
	v_mfma_f32_16x16x32_bf16 v[30:33], v[132:135], v[202:205], v[30:33]
	v_mfma_f32_16x16x32_bf16 v[30:33], v[136:139], v[218:221], v[30:33]
	v_mfma_f32_16x16x32_bf16 v[26:29], v[140:143], v[202:205], v[26:29]
	v_mfma_f32_16x16x32_bf16 v[26:29], v[144:147], v[218:221], v[26:29]
	v_mfma_f32_16x16x32_bf16 v[14:17], v[132:135], v[206:209], v[14:17]
	v_mfma_f32_16x16x32_bf16 v[14:17], v[136:139], v[222:225], v[14:17]
	v_mfma_f32_16x16x32_bf16 v[10:13], v[140:143], v[206:209], v[10:13]
	v_mfma_f32_16x16x32_bf16 v[10:13], v[144:147], v[222:225], v[10:13]
	s_setprio 0
	s_setprio 1
	s_cmp_lg_u32 s101, 0
	s_cbranch_scc1 .Lpad_m2
	v_mfma_f32_16x16x32_bf16 v[54:57], v[148:151], v[164:167], v[54:57]
	v_mfma_f32_16x16x32_bf16 v[54:57], v[152:155], v[194:197], v[54:57]
	v_mfma_f32_16x16x32_bf16 v[50:53], v[156:159], v[164:167], v[50:53]
	v_mfma_f32_16x16x32_bf16 v[50:53], v[160:163], v[194:197], v[50:53]
	v_mfma_f32_16x16x32_bf16 v[38:41], v[148:151], v[190:193], v[38:41]
	v_mfma_f32_16x16x32_bf16 v[38:41], v[152:155], v[198:201], v[38:41]
	v_mfma_f32_16x16x32_bf16 v[34:37], v[156:159], v[190:193], v[34:37]
	v_mfma_f32_16x16x32_bf16 v[34:37], v[160:163], v[198:201], v[34:37]
	v_mfma_f32_16x16x32_bf16 v[22:25], v[148:151], v[202:205], v[22:25]
	v_mfma_f32_16x16x32_bf16 v[22:25], v[152:155], v[218:221], v[22:25]
	v_mfma_f32_16x16x32_bf16 v[18:21], v[156:159], v[202:205], v[18:21]
	v_mfma_f32_16x16x32_bf16 v[18:21], v[160:163], v[218:221], v[18:21]
	v_mfma_f32_16x16x32_bf16 v[6:9], v[148:151], v[206:209], v[6:9]
	v_mfma_f32_16x16x32_bf16 v[6:9], v[152:155], v[222:225], v[6:9]
	v_mfma_f32_16x16x32_bf16 v[2:5], v[156:159], v[206:209], v[2:5]
	v_mfma_f32_16x16x32_bf16 v[2:5], v[160:163], v[222:225], v[2:5]
.Lpad_m2:
	s_setprio 0
	s_barrier
	s_add_i32 s43, 0, 0x18000
	s_add_i32 s46, 0, 0x1c000
	ds_read_b128 v[132:135], v245 offset:32768
	ds_read_b128 v[136:139], v246 offset:32768
	ds_read_b128 v[140:143], v245 offset:34816
	ds_read_b128 v[144:147], v246 offset:34816
	s_cmp_lg_u32 s101, 0
	s_cbranch_scc1 .Lpad_r2
	ds_read_b128 v[148:151], v245 offset:49152
	ds_read_b128 v[152:155], v246 offset:49152
	ds_read_b128 v[156:159], v245 offset:51200
	ds_read_b128 v[160:163], v246 offset:51200
.Lpad_r2:
	s_add_u32 s44, vcc_lo, 0x40000
	s_addc_u32 s45, vcc_hi, 0
	s_mov_b32 m0, s94
	ds_read_b128 v[164:167], v215 offset:32768
	ds_read_b128 v[190:193], v215 offset:34816
	ds_read_b128 v[194:197], v216 offset:32768
	ds_read_b128 v[198:201], v216 offset:34816
	ds_read_b128 v[202:205], v215 offset:36864
	ds_read_b128 v[206:209], v215 offset:38912
	ds_read_b128 v[218:221], v216 offset:36864
	ds_read_b128 v[222:225], v216 offset:38912
	global_load_lds_dwordx4 v174, s[44:45]
	s_mov_b32 m0, s95
	s_nop 0
	global_load_lds_dwordx4 v176, s[44:45]
	s_waitcnt vmcnt(8)
	s_waitcnt lgkmcnt(0)
	s_barrier
	s_setprio 1
	s_waitcnt lgkmcnt(0)
	v_mfma_f32_16x16x32_bf16 v[126:129], v[132:135], v[164:167], v[126:129]
	v_mfma_f32_16x16x32_bf16 v[126:129], v[136:139], v[194:197], v[126:129]
	v_mfma_f32_16x16x32_bf16 v[122:125], v[140:143], v[164:167], v[122:125]
	v_mfma_f32_16x16x32_bf16 v[122:125], v[144:147], v[194:197], v[122:125]
	v_mfma_f32_16x16x32_bf16 v[110:113], v[132:135], v[190:193], v[110:113]
	v_mfma_f32_16x16x32_bf16 v[110:113], v[136:139], v[198:201], v[110:113]
	v_mfma_f32_16x16x32_bf16 v[106:109], v[140:143], v[190:193], v[106:109]
	v_mfma_f32_16x16x32_bf16 v[106:109], v[144:147], v[198:201], v[106:109]
	v_mfma_f32_16x16x32_bf16 v[94:97], v[132:135], v[202:205], v[94:97]
	v_mfma_f32_16x16x32_bf16 v[94:97], v[136:139], v[218:221], v[94:97]
	v_mfma_f32_16x16x32_bf16 v[90:93], v[140:143], v[202:205], v[90:93]
	v_mfma_f32_16x16x32_bf16 v[90:93], v[144:147], v[218:221], v[90:93]
	v_mfma_f32_16x16x32_bf16 v[78:81], v[132:135], v[206:209], v[78:81]
	v_mfma_f32_16x16x32_bf16 v[78:81], v[136:139], v[222:225], v[78:81]
	v_mfma_f32_16x16x32_bf16 v[74:77], v[140:143], v[206:209], v[74:77]
	v_mfma_f32_16x16x32_bf16 v[74:77], v[144:147], v[222:225], v[74:77]
	s_setprio 0
	s_setprio 1
	s_cmp_lg_u32 s101, 0
	s_cbranch_scc1 .Lpad_m3
	v_mfma_f32_16x16x32_bf16 v[118:121], v[148:151], v[164:167], v[118:121]
	v_mfma_f32_16x16x32_bf16 v[118:121], v[152:155], v[194:197], v[118:121]
	v_mfma_f32_16x16x32_bf16 v[114:117], v[156:159], v[164:167], v[114:117]
	v_mfma_f32_16x16x32_bf16 v[114:117], v[160:163], v[194:197], v[114:117]
	v_mfma_f32_16x16x32_bf16 v[102:105], v[148:151], v[190:193], v[102:105]
	v_mfma_f32_16x16x32_bf16 v[102:105], v[152:155], v[198:201], v[102:105]
	v_mfma_f32_16x16x32_bf16 v[98:101], v[156:159], v[190:193], v[98:101]
	v_mfma_f32_16x16x32_bf16 v[98:101], v[160:163], v[198:201], v[98:101]
	v_mfma_f32_16x16x32_bf16 v[86:89], v[148:151], v[202:205], v[86:89]
	v_mfma_f32_16x16x32_bf16 v[86:89], v[152:155], v[218:221], v[86:89]
	v_mfma_f32_16x16x32_bf16 v[82:85], v[156:159], v[202:205], v[82:85]
	v_mfma_f32_16x16x32_bf16 v[82:85], v[160:163], v[218:221], v[82:85]
	v_mfma_f32_16x16x32_bf16 v[70:73], v[148:151], v[206:209], v[70:73]
	v_mfma_f32_16x16x32_bf16 v[70:73], v[152:155], v[222:225], v[70:73]
	v_mfma_f32_16x16x32_bf16 v[66:69], v[156:159], v[206:209], v[66:69]
	v_mfma_f32_16x16x32_bf16 v[66:69], v[160:163], v[222:225], v[66:69]
.Lpad_m3:
	s_setprio 0
	s_barrier
	s_add_i32 s43, s43, s15
	s_add_i32 m0, s43, 0xffffff80
	ds_read_b128 v[164:167], v215 offset:49152
	ds_read_b128 v[190:193], v215 offset:51200
	ds_read_b128 v[194:197], v216 offset:49152
	ds_read_b128 v[198:201], v216 offset:51200
	ds_read_b128 v[202:205], v215 offset:53248
	ds_read_b128 v[206:209], v215 offset:55296
	ds_read_b128 v[218:221], v216 offset:53248
	ds_read_b128 v[222:225], v216 offset:55296
	global_load_lds_dwordx4 v170, s[86:87] offset:128
	s_add_i32 m0, s43, 0x1f80
	s_add_u32 s44, s86, 0x40080
	s_addc_u32 s45, s87, 0
	s_add_i32 s43, s46, s15
	global_load_lds_dwordx4 v178, s[86:87] offset:128
	s_mov_b32 m0, s43
	s_nop 0
	global_load_lds_dwordx4 v170, s[44:45]
	s_add_i32 m0, s43, 0x2000
	s_nop 0
	global_load_lds_dwordx4 v178, s[44:45]
	s_add_i32 m0, s80, 0xffffff80
	s_nop 0
	global_load_lds_dwordx4 v174, vcc offset:128
	s_add_i32 m0, s81, 0xffffff80
	s_nop 0
	global_load_lds_dwordx4 v176, vcc offset:128
	s_waitcnt vmcnt(8)
	s_waitcnt lgkmcnt(0)
	s_barrier
	s_setprio 1
	s_waitcnt lgkmcnt(0)
	v_mfma_f32_16x16x32_bf16 v[62:65], v[132:135], v[164:167], v[62:65]
	v_mfma_f32_16x16x32_bf16 v[62:65], v[136:139], v[194:197], v[62:65]
	v_mfma_f32_16x16x32_bf16 v[58:61], v[140:143], v[164:167], v[58:61]
	v_mfma_f32_16x16x32_bf16 v[58:61], v[144:147], v[194:197], v[58:61]
	v_mfma_f32_16x16x32_bf16 v[46:49], v[132:135], v[190:193], v[46:49]
	v_mfma_f32_16x16x32_bf16 v[46:49], v[136:139], v[198:201], v[46:49]
	v_mfma_f32_16x16x32_bf16 v[42:45], v[140:143], v[190:193], v[42:45]
	v_mfma_f32_16x16x32_bf16 v[42:45], v[144:147], v[198:201], v[42:45]
	v_mfma_f32_16x16x32_bf16 v[30:33], v[132:135], v[202:205], v[30:33]
	v_mfma_f32_16x16x32_bf16 v[30:33], v[136:139], v[218:221], v[30:33]
	v_mfma_f32_16x16x32_bf16 v[26:29], v[140:143], v[202:205], v[26:29]
	v_mfma_f32_16x16x32_bf16 v[26:29], v[144:147], v[218:221], v[26:29]
	v_mfma_f32_16x16x32_bf16 v[14:17], v[132:135], v[206:209], v[14:17]
	v_mfma_f32_16x16x32_bf16 v[14:17], v[136:139], v[222:225], v[14:17]
	v_mfma_f32_16x16x32_bf16 v[10:13], v[140:143], v[206:209], v[10:13]
	v_mfma_f32_16x16x32_bf16 v[10:13], v[144:147], v[222:225], v[10:13]
	s_setprio 0
	s_setprio 1
	s_cmp_lg_u32 s101, 0
	s_cbranch_scc1 .Lpad_m4
	v_mfma_f32_16x16x32_bf16 v[54:57], v[148:151], v[164:167], v[54:57]
	v_mfma_f32_16x16x32_bf16 v[54:57], v[152:155], v[194:197], v[54:57]
	v_mfma_f32_16x16x32_bf16 v[50:53], v[156:159], v[164:167], v[50:53]
	v_mfma_f32_16x16x32_bf16 v[50:53], v[160:163], v[194:197], v[50:53]
	v_mfma_f32_16x16x32_bf16 v[38:41], v[148:151], v[190:193], v[38:41]
	v_mfma_f32_16x16x32_bf16 v[38:41], v[152:155], v[198:201], v[38:41]
	v_mfma_f32_16x16x32_bf16 v[34:37], v[156:159], v[190:193], v[34:37]
	v_mfma_f32_16x16x32_bf16 v[34:37], v[160:163], v[198:201], v[34:37]
	v_mfma_f32_16x16x32_bf16 v[22:25], v[148:151], v[202:205], v[22:25]
	v_mfma_f32_16x16x32_bf16 v[22:25], v[152:155], v[218:221], v[22:25]
	v_mfma_f32_16x16x32_bf16 v[18:21], v[156:159], v[202:205], v[18:21]
	v_mfma_f32_16x16x32_bf16 v[18:21], v[160:163], v[218:221], v[18:21]
	v_mfma_f32_16x16x32_bf16 v[6:9], v[148:151], v[206:209], v[6:9]
	v_mfma_f32_16x16x32_bf16 v[6:9], v[152:155], v[222:225], v[6:9]
	v_mfma_f32_16x16x32_bf16 v[2:5], v[156:159], v[206:209], v[2:5]
	v_mfma_f32_16x16x32_bf16 v[2:5], v[160:163], v[222:225], v[2:5]
.Lpad_m4:
	s_setprio 0
	s_barrier
	s_add_i32 s42, s42, 2
	s_add_u32 s10, s10, 0x100
	s_addc_u32 s11, s11, 0
	s_add_u32 s68, s68, 0x100
	s_addc_u32 s69, s69, 0
	s_cmp_gt_u32 s42, 13
	s_cbranch_scc1 .LBB0_688
